# GEMM unit loops: compiler-inserted vmcnt(0) flush before the K-loop (per-unit store drain) replaced by a nop; the template's own counted waits and barriers already order the LDS tiles
# speedup vs baseline: 1.0322x; 1.0011x over previous
.LBB0_174:
	s_ashr_i32 s15, s14, 31
	s_lshl_b64 s[16:17], s[14:15], 19
	s_add_u32 s16, s82, s16
	s_addc_u32 s17, s83, s17
	s_and_b64 s[18:19], s[0:1], exec
	s_cselect_b32 s15, s17, s23
	s_cselect_b32 s86, s16, s22
	s_ashr_i32 s13, s12, 31
	s_lshl_b64 s[18:19], s[12:13], 19
	s_add_u32 s18, s33, s18
	s_addc_u32 s19, s38, s19
	s_and_b64 s[26:27], s[0:1], exec
	s_cselect_b32 s13, s19, s25
	s_cselect_b32 s87, s18, s24
	s_add_u32 s22, s22, 0x40080
	s_addc_u32 s23, s23, 0
	s_add_u32 s88, s24, 0x100
	v_mov_b32_e32 v0, 0
	s_addc_u32 s89, s25, 0
	s_mov_b32 s90, -2
	v_mov_b32_e32 v1, v0
	v_mov_b32_e32 v2, v0
	v_mov_b32_e32 v3, v0
	v_mov_b32_e32 v4, v0
	v_mov_b32_e32 v5, v0
	v_mov_b32_e32 v6, v0
	v_mov_b32_e32 v7, v0
	s_nop 0
	v_mov_b32_e32 v16, v0
	v_mov_b32_e32 v17, v0
	v_mov_b32_e32 v18, v0
	v_mov_b32_e32 v19, v0
	v_mov_b32_e32 v20, v0
	v_mov_b32_e32 v21, v0
	v_mov_b32_e32 v22, v0
	v_mov_b32_e32 v23, v0
	v_mov_b32_e32 v32, v0
	v_mov_b32_e32 v33, v0
	v_mov_b32_e32 v34, v0
	v_mov_b32_e32 v35, v0
	v_mov_b32_e32 v36, v0
	v_mov_b32_e32 v37, v0
	v_mov_b32_e32 v38, v0
	v_mov_b32_e32 v39, v0
	v_mov_b32_e32 v48, v0
	v_mov_b32_e32 v49, v0
	v_mov_b32_e32 v50, v0
	v_mov_b32_e32 v51, v0
	v_mov_b32_e32 v52, v0
	v_mov_b32_e32 v53, v0
	v_mov_b32_e32 v54, v0
	v_mov_b32_e32 v55, v0
	v_mov_b32_e32 v8, v0
	v_mov_b32_e32 v9, v0
	v_mov_b32_e32 v10, v0
	v_mov_b32_e32 v11, v0
	v_mov_b32_e32 v12, v0
	v_mov_b32_e32 v13, v0
	v_mov_b32_e32 v14, v0
	v_mov_b32_e32 v15, v0
	v_mov_b32_e32 v24, v0
	v_mov_b32_e32 v25, v0
	v_mov_b32_e32 v26, v0
	v_mov_b32_e32 v27, v0
	v_mov_b32_e32 v28, v0
	v_mov_b32_e32 v29, v0
	v_mov_b32_e32 v30, v0
	v_mov_b32_e32 v31, v0
	v_mov_b32_e32 v40, v0
	v_mov_b32_e32 v41, v0
	v_mov_b32_e32 v42, v0
	v_mov_b32_e32 v43, v0
	v_mov_b32_e32 v44, v0
	v_mov_b32_e32 v45, v0
	v_mov_b32_e32 v46, v0
	v_mov_b32_e32 v47, v0
	v_mov_b32_e32 v56, v0
	v_mov_b32_e32 v57, v0
	v_mov_b32_e32 v58, v0
	v_mov_b32_e32 v59, v0
	v_mov_b32_e32 v60, v0
	v_mov_b32_e32 v61, v0
	v_mov_b32_e32 v62, v0
	v_mov_b32_e32 v63, v0
	v_mov_b32_e32 v64, v0
	v_mov_b32_e32 v65, v0
	v_mov_b32_e32 v66, v0
	v_mov_b32_e32 v67, v0
	v_mov_b32_e32 v68, v0
	v_mov_b32_e32 v69, v0
	v_mov_b32_e32 v70, v0
	v_mov_b32_e32 v71, v0
	v_mov_b32_e32 v80, v0
	v_mov_b32_e32 v81, v0
	v_mov_b32_e32 v82, v0
	v_mov_b32_e32 v83, v0
	v_mov_b32_e32 v84, v0
	v_mov_b32_e32 v85, v0
	v_mov_b32_e32 v86, v0
	v_mov_b32_e32 v87, v0
	v_mov_b32_e32 v88, v0
	v_mov_b32_e32 v89, v0
	v_mov_b32_e32 v90, v0
	v_mov_b32_e32 v91, v0
	v_mov_b32_e32 v92, v0
	v_mov_b32_e32 v93, v0
	v_mov_b32_e32 v94, v0
	v_mov_b32_e32 v95, v0
	v_mov_b32_e32 v100, v0
	v_mov_b32_e32 v101, v0
	v_mov_b32_e32 v102, v0
	v_mov_b32_e32 v103, v0
	v_mov_b32_e32 v108, v0
	v_mov_b32_e32 v109, v0
	v_mov_b32_e32 v110, v0
	v_mov_b32_e32 v111, v0
	v_mov_b32_e32 v72, v0
	v_mov_b32_e32 v73, v0
	v_mov_b32_e32 v74, v0
	v_mov_b32_e32 v75, v0
	v_mov_b32_e32 v76, v0
	v_mov_b32_e32 v77, v0
	v_mov_b32_e32 v78, v0
	v_mov_b32_e32 v79, v0
	v_mov_b32_e32 v96, v0
	v_mov_b32_e32 v97, v0
	v_mov_b32_e32 v98, v0
	v_mov_b32_e32 v99, v0
	v_mov_b32_e32 v104, v0
	v_mov_b32_e32 v105, v0
	v_mov_b32_e32 v106, v0
	v_mov_b32_e32 v107, v0
	v_mov_b32_e32 v112, v0
	v_mov_b32_e32 v113, v0
	v_mov_b32_e32 v114, v0
	v_mov_b32_e32 v115, v0
	v_mov_b32_e32 v116, v0
	v_mov_b32_e32 v117, v0
	v_mov_b32_e32 v118, v0
	v_mov_b32_e32 v119, v0
	v_mov_b32_e32 v120, v0
	v_mov_b32_e32 v121, v0
	v_mov_b32_e32 v122, v0
	v_mov_b32_e32 v123, v0
	v_mov_b32_e32 v124, v0
	v_mov_b32_e32 v125, v0
	v_mov_b32_e32 v126, v0
	v_mov_b32_e32 v127, v0

.LBB0_198:
	s_ashr_i32 s15, s14, 31
	s_lshl_b64 s[16:17], s[14:15], 19
	s_add_u32 s16, s31, s16
	s_addc_u32 s17, s34, s17
	s_and_b64 s[18:19], s[0:1], exec
	s_cselect_b32 s15, s17, s23
	s_cselect_b32 s88, s16, s22
	s_ashr_i32 s13, s12, 31
	s_lshl_b64 s[18:19], s[12:13], 19
	s_add_u32 s18, s82, s18
	s_addc_u32 s19, s83, s19
	s_and_b64 s[26:27], s[0:1], exec
	s_cselect_b32 s13, s19, s25
	s_cselect_b32 s89, s18, s24
	s_add_u32 s22, s22, 0x40080
	s_addc_u32 s23, s23, 0
	s_add_u32 s90, s24, 0x100
	v_mov_b32_e32 v0, 0
	s_addc_u32 s91, s25, 0
	s_mov_b32 s92, -2
	v_mov_b32_e32 v1, v0
	v_mov_b32_e32 v2, v0
	v_mov_b32_e32 v3, v0
	v_mov_b32_e32 v4, v0
	v_mov_b32_e32 v5, v0
	v_mov_b32_e32 v6, v0
	v_mov_b32_e32 v7, v0
	v_mov_b32_e32 v12, v0
	v_mov_b32_e32 v13, v0
	v_mov_b32_e32 v14, v0
	v_mov_b32_e32 v15, v0
	s_nop 0
	v_mov_b32_e32 v20, v0
	v_mov_b32_e32 v21, v0
	v_mov_b32_e32 v22, v0
	v_mov_b32_e32 v23, v0
	v_mov_b32_e32 v28, v0
	v_mov_b32_e32 v29, v0
	v_mov_b32_e32 v30, v0
	v_mov_b32_e32 v31, v0
	v_mov_b32_e32 v36, v0
	v_mov_b32_e32 v37, v0
	v_mov_b32_e32 v38, v0
	v_mov_b32_e32 v39, v0
	v_mov_b32_e32 v44, v0
	v_mov_b32_e32 v45, v0
	v_mov_b32_e32 v46, v0
	v_mov_b32_e32 v47, v0
	v_mov_b32_e32 v52, v0
	v_mov_b32_e32 v53, v0
	v_mov_b32_e32 v54, v0
	v_mov_b32_e32 v55, v0
	v_mov_b32_e32 v8, v0
	v_mov_b32_e32 v9, v0
	v_mov_b32_e32 v10, v0
	v_mov_b32_e32 v11, v0
	v_mov_b32_e32 v16, v0
	v_mov_b32_e32 v17, v0
	v_mov_b32_e32 v18, v0
	v_mov_b32_e32 v19, v0
	v_mov_b32_e32 v24, v0
	v_mov_b32_e32 v25, v0
	v_mov_b32_e32 v26, v0
	v_mov_b32_e32 v27, v0
	v_mov_b32_e32 v32, v0
	v_mov_b32_e32 v33, v0
	v_mov_b32_e32 v34, v0
	v_mov_b32_e32 v35, v0
	v_mov_b32_e32 v40, v0
	v_mov_b32_e32 v41, v0
	v_mov_b32_e32 v42, v0
	v_mov_b32_e32 v43, v0
	v_mov_b32_e32 v48, v0
	v_mov_b32_e32 v49, v0
	v_mov_b32_e32 v50, v0
	v_mov_b32_e32 v51, v0
	v_mov_b32_e32 v56, v0
	v_mov_b32_e32 v57, v0
	v_mov_b32_e32 v58, v0
	v_mov_b32_e32 v59, v0
	v_mov_b32_e32 v60, v0
	v_mov_b32_e32 v61, v0
	v_mov_b32_e32 v62, v0
	v_mov_b32_e32 v63, v0
	v_mov_b32_e32 v64, v0
	v_mov_b32_e32 v65, v0
	v_mov_b32_e32 v66, v0
	v_mov_b32_e32 v67, v0
	v_mov_b32_e32 v68, v0
	v_mov_b32_e32 v69, v0
	v_mov_b32_e32 v70, v0
	v_mov_b32_e32 v71, v0
	v_mov_b32_e32 v76, v0
	v_mov_b32_e32 v77, v0
	v_mov_b32_e32 v78, v0
	v_mov_b32_e32 v79, v0
	v_mov_b32_e32 v84, v0
	v_mov_b32_e32 v85, v0
	v_mov_b32_e32 v86, v0
	v_mov_b32_e32 v87, v0
	v_mov_b32_e32 v92, v0
	v_mov_b32_e32 v93, v0
	v_mov_b32_e32 v94, v0
	v_mov_b32_e32 v95, v0
	v_mov_b32_e32 v96, v0
	v_mov_b32_e32 v97, v0
	v_mov_b32_e32 v98, v0
	v_mov_b32_e32 v99, v0
	v_mov_b32_e32 v100, v0
	v_mov_b32_e32 v101, v0
	v_mov_b32_e32 v102, v0
	v_mov_b32_e32 v103, v0
	v_mov_b32_e32 v104, v0
	v_mov_b32_e32 v105, v0
	v_mov_b32_e32 v106, v0
	v_mov_b32_e32 v107, v0
	v_mov_b32_e32 v72, v0
	v_mov_b32_e32 v73, v0
	v_mov_b32_e32 v74, v0
	v_mov_b32_e32 v75, v0
	v_mov_b32_e32 v80, v0
	v_mov_b32_e32 v81, v0
	v_mov_b32_e32 v82, v0
	v_mov_b32_e32 v83, v0
	v_mov_b32_e32 v88, v0
	v_mov_b32_e32 v89, v0
	v_mov_b32_e32 v90, v0
	v_mov_b32_e32 v91, v0
	v_mov_b32_e32 v108, v0
	v_mov_b32_e32 v109, v0
	v_mov_b32_e32 v110, v0
	v_mov_b32_e32 v111, v0
	v_mov_b32_e32 v112, v0
	v_mov_b32_e32 v113, v0
	v_mov_b32_e32 v114, v0
	v_mov_b32_e32 v115, v0
	v_mov_b32_e32 v116, v0
	v_mov_b32_e32 v117, v0
	v_mov_b32_e32 v118, v0
	v_mov_b32_e32 v119, v0
	v_mov_b32_e32 v120, v0
	v_mov_b32_e32 v121, v0
	v_mov_b32_e32 v122, v0
	v_mov_b32_e32 v123, v0
	v_mov_b32_e32 v124, v0
	v_mov_b32_e32 v125, v0
	v_mov_b32_e32 v126, v0
	v_mov_b32_e32 v127, v0

.LBB0_521:
	s_ashr_i32 s17, s16, 31
	s_lshl_b64 s[18:19], s[16:17], 19
	s_add_u32 s18, s84, s18
	s_addc_u32 s19, s85, s19
	s_and_b64 s[20:21], s[4:5], exec
	s_cselect_b32 s3, s19, s27
	s_cselect_b32 s17, s18, s26
	s_ashr_i32 s15, s14, 31
	s_lshl_b64 s[20:21], s[14:15], 19
	s_add_u32 s20, s39, s20
	s_addc_u32 s21, s50, s21
	s_and_b64 s[30:31], s[4:5], exec
	s_cselect_b32 s15, s21, s29
	s_cselect_b32 s23, s20, s28
	s_add_u32 s92, s28, 0x100
	v_mov_b32_e32 v0, 0
	s_addc_u32 s93, s29, 0
	s_mov_b32 s94, -2
	s_waitcnt lgkmcnt(0)
	v_mov_b32_e32 v1, v0
	v_mov_b32_e32 v2, v0
	v_mov_b32_e32 v3, v0
	v_mov_b32_e32 v4, v0
	v_mov_b32_e32 v5, v0
	v_mov_b32_e32 v6, v0
	v_mov_b32_e32 v7, v0
	v_mov_b32_e32 v16, v0
	v_mov_b32_e32 v17, v0
	v_mov_b32_e32 v18, v0
	v_mov_b32_e32 v19, v0
	s_nop 0
	v_mov_b32_e32 v20, v0
	v_mov_b32_e32 v21, v0
	v_mov_b32_e32 v22, v0
	v_mov_b32_e32 v23, v0
	v_mov_b32_e32 v32, v0
	v_mov_b32_e32 v33, v0
	v_mov_b32_e32 v34, v0
	v_mov_b32_e32 v35, v0
	v_mov_b32_e32 v36, v0
	v_mov_b32_e32 v37, v0
	v_mov_b32_e32 v38, v0
	v_mov_b32_e32 v39, v0
	v_mov_b32_e32 v48, v0
	v_mov_b32_e32 v49, v0
	v_mov_b32_e32 v50, v0
	v_mov_b32_e32 v51, v0
	v_mov_b32_e32 v52, v0
	v_mov_b32_e32 v53, v0
	v_mov_b32_e32 v54, v0
	v_mov_b32_e32 v55, v0
	v_mov_b32_e32 v8, v0
	v_mov_b32_e32 v9, v0
	v_mov_b32_e32 v10, v0
	v_mov_b32_e32 v11, v0
	v_mov_b32_e32 v12, v0
	v_mov_b32_e32 v13, v0
	v_mov_b32_e32 v14, v0
	v_mov_b32_e32 v15, v0
	v_mov_b32_e32 v24, v0
	v_mov_b32_e32 v25, v0
	v_mov_b32_e32 v26, v0
	v_mov_b32_e32 v27, v0
	v_mov_b32_e32 v28, v0
	v_mov_b32_e32 v29, v0
	v_mov_b32_e32 v30, v0
	v_mov_b32_e32 v31, v0
	v_mov_b32_e32 v40, v0
	v_mov_b32_e32 v41, v0
	v_mov_b32_e32 v42, v0
	v_mov_b32_e32 v43, v0
	v_mov_b32_e32 v44, v0
	v_mov_b32_e32 v45, v0
	v_mov_b32_e32 v46, v0
	v_mov_b32_e32 v47, v0
	v_mov_b32_e32 v56, v0
	v_mov_b32_e32 v57, v0
	v_mov_b32_e32 v58, v0
	v_mov_b32_e32 v59, v0
	v_mov_b32_e32 v60, v0
	v_mov_b32_e32 v61, v0
	v_mov_b32_e32 v62, v0
	v_mov_b32_e32 v63, v0
	v_mov_b32_e32 v64, v0
	v_mov_b32_e32 v65, v0
	v_mov_b32_e32 v66, v0
	v_mov_b32_e32 v67, v0
	v_mov_b32_e32 v68, v0
	v_mov_b32_e32 v69, v0
	v_mov_b32_e32 v70, v0
	v_mov_b32_e32 v71, v0
	v_mov_b32_e32 v80, v0
	v_mov_b32_e32 v81, v0
	v_mov_b32_e32 v82, v0
	v_mov_b32_e32 v83, v0
	v_mov_b32_e32 v84, v0
	v_mov_b32_e32 v85, v0
	v_mov_b32_e32 v86, v0
	v_mov_b32_e32 v87, v0
	v_mov_b32_e32 v96, v0
	v_mov_b32_e32 v97, v0
	v_mov_b32_e32 v98, v0
	v_mov_b32_e32 v99, v0
	v_mov_b32_e32 v100, v0
	v_mov_b32_e32 v101, v0
	v_mov_b32_e32 v102, v0
	v_mov_b32_e32 v103, v0
	v_mov_b32_e32 v112, v0
	v_mov_b32_e32 v113, v0
	v_mov_b32_e32 v114, v0
	v_mov_b32_e32 v115, v0
	v_mov_b32_e32 v116, v0
	v_mov_b32_e32 v117, v0
	v_mov_b32_e32 v118, v0
	v_mov_b32_e32 v119, v0
	v_mov_b32_e32 v72, v0
	v_mov_b32_e32 v73, v0
	v_mov_b32_e32 v74, v0
	v_mov_b32_e32 v75, v0
	v_mov_b32_e32 v76, v0
	v_mov_b32_e32 v77, v0
	v_mov_b32_e32 v78, v0
	v_mov_b32_e32 v79, v0
	v_mov_b32_e32 v88, v0
	v_mov_b32_e32 v89, v0
	v_mov_b32_e32 v90, v0
	v_mov_b32_e32 v91, v0
	v_mov_b32_e32 v92, v0
	v_mov_b32_e32 v93, v0
	v_mov_b32_e32 v94, v0
	v_mov_b32_e32 v95, v0
	v_mov_b32_e32 v104, v0
	v_mov_b32_e32 v105, v0
	v_mov_b32_e32 v106, v0
	v_mov_b32_e32 v107, v0
	v_mov_b32_e32 v108, v0
	v_mov_b32_e32 v109, v0
	v_mov_b32_e32 v110, v0
	v_mov_b32_e32 v111, v0
	v_mov_b32_e32 v120, v0
	v_mov_b32_e32 v121, v0
	v_mov_b32_e32 v122, v0
	v_mov_b32_e32 v123, v0
	v_mov_b32_e32 v124, v0
	v_mov_b32_e32 v125, v0
	v_mov_b32_e32 v126, v0
	v_mov_b32_e32 v127, v0

.LBB0_693:
	s_ashr_i32 s17, s16, 31
	s_lshl_b64 s[18:19], s[16:17], 19
	s_add_u32 s18, s82, s18
	s_addc_u32 s19, s83, s19
	s_and_b64 s[20:21], s[0:1], exec
	s_cselect_b32 s17, s19, s25
	s_cselect_b32 s87, s18, s24
	s_ashr_i32 s15, s14, 31
	s_lshl_b64 s[20:21], s[14:15], 19
	s_add_u32 s20, s35, s20
	s_addc_u32 s21, s36, s21
	s_and_b64 s[28:29], s[0:1], exec
	s_cselect_b32 s15, s21, s27
	s_cselect_b32 s88, s20, s26
	s_add_u32 s24, s24, 0x40080
	s_addc_u32 s25, s25, 0
	s_add_u32 s89, s26, 0x100
	v_mov_b32_e32 v0, 0
	s_addc_u32 s90, s27, 0
	s_mov_b32 s91, -2
	v_mov_b32_e32 v1, v0
	v_mov_b32_e32 v2, v0
	v_mov_b32_e32 v3, v0
	v_mov_b32_e32 v4, v0
	v_mov_b32_e32 v5, v0
	v_mov_b32_e32 v6, v0
	v_mov_b32_e32 v7, v0
	s_nop 0
	v_mov_b32_e32 v16, v0
	v_mov_b32_e32 v17, v0
	v_mov_b32_e32 v18, v0
	v_mov_b32_e32 v19, v0
	v_mov_b32_e32 v20, v0
	v_mov_b32_e32 v21, v0
	v_mov_b32_e32 v22, v0
	v_mov_b32_e32 v23, v0
	v_mov_b32_e32 v32, v0
	v_mov_b32_e32 v33, v0
	v_mov_b32_e32 v34, v0
	v_mov_b32_e32 v35, v0
	v_mov_b32_e32 v36, v0
	v_mov_b32_e32 v37, v0
	v_mov_b32_e32 v38, v0
	v_mov_b32_e32 v39, v0
	v_mov_b32_e32 v48, v0
	v_mov_b32_e32 v49, v0
	v_mov_b32_e32 v50, v0
	v_mov_b32_e32 v51, v0
	v_mov_b32_e32 v52, v0
	v_mov_b32_e32 v53, v0
	v_mov_b32_e32 v54, v0
	v_mov_b32_e32 v55, v0
	v_mov_b32_e32 v8, v0
	v_mov_b32_e32 v9, v0
	v_mov_b32_e32 v10, v0
	v_mov_b32_e32 v11, v0
	v_mov_b32_e32 v12, v0
	v_mov_b32_e32 v13, v0
	v_mov_b32_e32 v14, v0
	v_mov_b32_e32 v15, v0
	v_mov_b32_e32 v24, v0
	v_mov_b32_e32 v25, v0
	v_mov_b32_e32 v26, v0
	v_mov_b32_e32 v27, v0
	v_mov_b32_e32 v28, v0
	v_mov_b32_e32 v29, v0
	v_mov_b32_e32 v30, v0
	v_mov_b32_e32 v31, v0
	v_mov_b32_e32 v40, v0
	v_mov_b32_e32 v41, v0
	v_mov_b32_e32 v42, v0
	v_mov_b32_e32 v43, v0
	v_mov_b32_e32 v44, v0
	v_mov_b32_e32 v45, v0
	v_mov_b32_e32 v46, v0
	v_mov_b32_e32 v47, v0
	v_mov_b32_e32 v56, v0
	v_mov_b32_e32 v57, v0
	v_mov_b32_e32 v58, v0
	v_mov_b32_e32 v59, v0
	v_mov_b32_e32 v60, v0
	v_mov_b32_e32 v61, v0
	v_mov_b32_e32 v62, v0
	v_mov_b32_e32 v63, v0
	v_mov_b32_e32 v64, v0
	v_mov_b32_e32 v65, v0
	v_mov_b32_e32 v66, v0
	v_mov_b32_e32 v67, v0
	v_mov_b32_e32 v68, v0
	v_mov_b32_e32 v69, v0
	v_mov_b32_e32 v70, v0
	v_mov_b32_e32 v71, v0
	v_mov_b32_e32 v80, v0
	v_mov_b32_e32 v81, v0
	v_mov_b32_e32 v82, v0
	v_mov_b32_e32 v83, v0
	v_mov_b32_e32 v84, v0
	v_mov_b32_e32 v85, v0
	v_mov_b32_e32 v86, v0
	v_mov_b32_e32 v87, v0
	v_mov_b32_e32 v96, v0
	v_mov_b32_e32 v97, v0
	v_mov_b32_e32 v98, v0
	v_mov_b32_e32 v99, v0
	v_mov_b32_e32 v100, v0
	v_mov_b32_e32 v101, v0
	v_mov_b32_e32 v102, v0
	v_mov_b32_e32 v103, v0
	v_mov_b32_e32 v108, v0
	v_mov_b32_e32 v109, v0
	v_mov_b32_e32 v110, v0
	v_mov_b32_e32 v111, v0
	v_mov_b32_e32 v112, v0
	v_mov_b32_e32 v113, v0
	v_mov_b32_e32 v114, v0
	v_mov_b32_e32 v115, v0
	v_mov_b32_e32 v72, v0
	v_mov_b32_e32 v73, v0
	v_mov_b32_e32 v74, v0
	v_mov_b32_e32 v75, v0
	v_mov_b32_e32 v76, v0
	v_mov_b32_e32 v77, v0
	v_mov_b32_e32 v78, v0
	v_mov_b32_e32 v79, v0
	v_mov_b32_e32 v88, v0
	v_mov_b32_e32 v89, v0
	v_mov_b32_e32 v90, v0
	v_mov_b32_e32 v91, v0
	v_mov_b32_e32 v92, v0
	v_mov_b32_e32 v93, v0
	v_mov_b32_e32 v94, v0
	v_mov_b32_e32 v95, v0
	v_mov_b32_e32 v104, v0
	v_mov_b32_e32 v105, v0
	v_mov_b32_e32 v106, v0
	v_mov_b32_e32 v107, v0
	v_mov_b32_e32 v116, v0
	v_mov_b32_e32 v117, v0
	v_mov_b32_e32 v118, v0
	v_mov_b32_e32 v119, v0
	v_mov_b32_e32 v120, v0
	v_mov_b32_e32 v121, v0
	v_mov_b32_e32 v122, v0
	v_mov_b32_e32 v123, v0
	v_mov_b32_e32 v124, v0
	v_mov_b32_e32 v125, v0
	v_mov_b32_e32 v126, v0
	v_mov_b32_e32 v127, v0

.LBB0_851:
	s_ashr_i32 s17, s16, 31
	s_lshl_b64 s[18:19], s[16:17], 21
	s_add_u32 s18, s80, s18
	s_addc_u32 s19, s81, s19
	s_and_b64 s[20:21], s[4:5], exec
	s_cselect_b32 s3, s19, s27
	s_cselect_b32 s17, s18, s26
	s_ashr_i32 s15, s14, 31
	s_lshl_b64 s[20:21], s[14:15], 21
	s_add_u32 s20, s39, s20
	s_addc_u32 s21, s40, s21
	s_and_b64 s[30:31], s[4:5], exec
	s_cselect_b32 s15, s21, s29
	s_cselect_b32 s23, s20, s28
	s_add_u32 s90, s28, 0x100
	v_mov_b32_e32 v0, 0
	s_addc_u32 s91, s29, 0
	s_mov_b32 s92, -2
	s_waitcnt lgkmcnt(0)
	v_mov_b32_e32 v1, v0
	v_mov_b32_e32 v2, v0
	v_mov_b32_e32 v3, v0
	v_mov_b32_e32 v4, v0
	v_mov_b32_e32 v5, v0
	v_mov_b32_e32 v6, v0
	v_mov_b32_e32 v7, v0
	v_mov_b32_e32 v16, v0
	v_mov_b32_e32 v17, v0
	v_mov_b32_e32 v18, v0
	v_mov_b32_e32 v19, v0
	s_nop 0
	v_mov_b32_e32 v20, v0
	v_mov_b32_e32 v21, v0
	v_mov_b32_e32 v22, v0
	v_mov_b32_e32 v23, v0
	v_mov_b32_e32 v32, v0
	v_mov_b32_e32 v33, v0
	v_mov_b32_e32 v34, v0
	v_mov_b32_e32 v35, v0
	v_mov_b32_e32 v36, v0
	v_mov_b32_e32 v37, v0
	v_mov_b32_e32 v38, v0
	v_mov_b32_e32 v39, v0
	v_mov_b32_e32 v48, v0
	v_mov_b32_e32 v49, v0
	v_mov_b32_e32 v50, v0
	v_mov_b32_e32 v51, v0
	v_mov_b32_e32 v52, v0
	v_mov_b32_e32 v53, v0
	v_mov_b32_e32 v54, v0
	v_mov_b32_e32 v55, v0
	v_mov_b32_e32 v8, v0
	v_mov_b32_e32 v9, v0
	v_mov_b32_e32 v10, v0
	v_mov_b32_e32 v11, v0
	v_mov_b32_e32 v12, v0
	v_mov_b32_e32 v13, v0
	v_mov_b32_e32 v14, v0
	v_mov_b32_e32 v15, v0
	v_mov_b32_e32 v24, v0
	v_mov_b32_e32 v25, v0
	v_mov_b32_e32 v26, v0
	v_mov_b32_e32 v27, v0
	v_mov_b32_e32 v28, v0
	v_mov_b32_e32 v29, v0
	v_mov_b32_e32 v30, v0
	v_mov_b32_e32 v31, v0
	v_mov_b32_e32 v40, v0
	v_mov_b32_e32 v41, v0
	v_mov_b32_e32 v42, v0
	v_mov_b32_e32 v43, v0
	v_mov_b32_e32 v44, v0
	v_mov_b32_e32 v45, v0
	v_mov_b32_e32 v46, v0
	v_mov_b32_e32 v47, v0
	v_mov_b32_e32 v56, v0
	v_mov_b32_e32 v57, v0
	v_mov_b32_e32 v58, v0
	v_mov_b32_e32 v59, v0
	v_mov_b32_e32 v60, v0
	v_mov_b32_e32 v61, v0
	v_mov_b32_e32 v62, v0
	v_mov_b32_e32 v63, v0
	v_mov_b32_e32 v64, v0
	v_mov_b32_e32 v65, v0
	v_mov_b32_e32 v66, v0
	v_mov_b32_e32 v67, v0
	v_mov_b32_e32 v68, v0
	v_mov_b32_e32 v69, v0
	v_mov_b32_e32 v70, v0
	v_mov_b32_e32 v71, v0
	v_mov_b32_e32 v80, v0
	v_mov_b32_e32 v81, v0
	v_mov_b32_e32 v82, v0
	v_mov_b32_e32 v83, v0
	v_mov_b32_e32 v84, v0
	v_mov_b32_e32 v85, v0
	v_mov_b32_e32 v86, v0
	v_mov_b32_e32 v87, v0
	v_mov_b32_e32 v96, v0
	v_mov_b32_e32 v97, v0
	v_mov_b32_e32 v98, v0
	v_mov_b32_e32 v99, v0
	v_mov_b32_e32 v100, v0
	v_mov_b32_e32 v101, v0
	v_mov_b32_e32 v102, v0
	v_mov_b32_e32 v103, v0
	v_mov_b32_e32 v112, v0
	v_mov_b32_e32 v113, v0
	v_mov_b32_e32 v114, v0
	v_mov_b32_e32 v115, v0
	v_mov_b32_e32 v116, v0
	v_mov_b32_e32 v117, v0
	v_mov_b32_e32 v118, v0
	v_mov_b32_e32 v119, v0
	v_mov_b32_e32 v72, v0
	v_mov_b32_e32 v73, v0
	v_mov_b32_e32 v74, v0
	v_mov_b32_e32 v75, v0
	v_mov_b32_e32 v76, v0
	v_mov_b32_e32 v77, v0
	v_mov_b32_e32 v78, v0
	v_mov_b32_e32 v79, v0
	v_mov_b32_e32 v88, v0
	v_mov_b32_e32 v89, v0
	v_mov_b32_e32 v90, v0
	v_mov_b32_e32 v91, v0
	v_mov_b32_e32 v92, v0
	v_mov_b32_e32 v93, v0
	v_mov_b32_e32 v94, v0
	v_mov_b32_e32 v95, v0
	v_mov_b32_e32 v104, v0
	v_mov_b32_e32 v105, v0
	v_mov_b32_e32 v106, v0
	v_mov_b32_e32 v107, v0
	v_mov_b32_e32 v108, v0
	v_mov_b32_e32 v109, v0
	v_mov_b32_e32 v110, v0
	v_mov_b32_e32 v111, v0
	v_mov_b32_e32 v120, v0
	v_mov_b32_e32 v121, v0
	v_mov_b32_e32 v122, v0
	v_mov_b32_e32 v123, v0
	v_mov_b32_e32 v124, v0
	v_mov_b32_e32 v125, v0
	v_mov_b32_e32 v126, v0
	v_mov_b32_e32 v127, v0

.LBB0_1015:
	s_ashr_i32 s15, s14, 31
	s_lshl_b64 s[16:17], s[14:15], 19
	s_add_u32 s16, s82, s16
	s_addc_u32 s17, s83, s17
	s_and_b64 s[18:19], s[0:1], exec
	s_cselect_b32 s15, s17, s23
	s_cselect_b32 s48, s16, s22
	s_ashr_i32 s13, s12, 31
	s_lshl_b64 s[18:19], s[12:13], 19
	s_add_u32 s18, s30, s18
	s_addc_u32 s19, s31, s19
	s_and_b64 s[26:27], s[0:1], exec
	s_cselect_b32 s13, s19, s25
	s_cselect_b32 s49, s18, s24
	s_add_u32 s22, s22, 0x40080
	s_addc_u32 s23, s23, 0
	s_add_u32 s50, s24, 0x100
	v_mov_b32_e32 v0, 0
	s_addc_u32 s51, s25, 0
	s_mov_b32 s52, -2
	v_mov_b32_e32 v1, v0
	v_mov_b32_e32 v2, v0
	v_mov_b32_e32 v3, v0
	v_mov_b32_e32 v4, v0
	v_mov_b32_e32 v5, v0
	v_mov_b32_e32 v6, v0
	v_mov_b32_e32 v7, v0
	s_nop 0
	v_mov_b32_e32 v16, v0
	v_mov_b32_e32 v17, v0
	v_mov_b32_e32 v18, v0
	v_mov_b32_e32 v19, v0
	v_mov_b32_e32 v20, v0
	v_mov_b32_e32 v21, v0
	v_mov_b32_e32 v22, v0
	v_mov_b32_e32 v23, v0
	v_mov_b32_e32 v32, v0
	v_mov_b32_e32 v33, v0
	v_mov_b32_e32 v34, v0
	v_mov_b32_e32 v35, v0
	v_mov_b32_e32 v36, v0
	v_mov_b32_e32 v37, v0
	v_mov_b32_e32 v38, v0
	v_mov_b32_e32 v39, v0
	v_mov_b32_e32 v48, v0
	v_mov_b32_e32 v49, v0
	v_mov_b32_e32 v50, v0
	v_mov_b32_e32 v51, v0
	v_mov_b32_e32 v52, v0
	v_mov_b32_e32 v53, v0
	v_mov_b32_e32 v54, v0
	v_mov_b32_e32 v55, v0
	v_mov_b32_e32 v8, v0
	v_mov_b32_e32 v9, v0
	v_mov_b32_e32 v10, v0
	v_mov_b32_e32 v11, v0
	v_mov_b32_e32 v12, v0
	v_mov_b32_e32 v13, v0
	v_mov_b32_e32 v14, v0
	v_mov_b32_e32 v15, v0
	v_mov_b32_e32 v24, v0
	v_mov_b32_e32 v25, v0
	v_mov_b32_e32 v26, v0
	v_mov_b32_e32 v27, v0
	v_mov_b32_e32 v28, v0
	v_mov_b32_e32 v29, v0
	v_mov_b32_e32 v30, v0
	v_mov_b32_e32 v31, v0
	v_mov_b32_e32 v40, v0
	v_mov_b32_e32 v41, v0
	v_mov_b32_e32 v42, v0
	v_mov_b32_e32 v43, v0
	v_mov_b32_e32 v44, v0
	v_mov_b32_e32 v45, v0
	v_mov_b32_e32 v46, v0
	v_mov_b32_e32 v47, v0
	v_mov_b32_e32 v56, v0
	v_mov_b32_e32 v57, v0
	v_mov_b32_e32 v58, v0
	v_mov_b32_e32 v59, v0
	v_mov_b32_e32 v60, v0
	v_mov_b32_e32 v61, v0
	v_mov_b32_e32 v62, v0
	v_mov_b32_e32 v63, v0
	v_mov_b32_e32 v64, v0
	v_mov_b32_e32 v65, v0
	v_mov_b32_e32 v66, v0
	v_mov_b32_e32 v67, v0
	v_mov_b32_e32 v68, v0
	v_mov_b32_e32 v69, v0
	v_mov_b32_e32 v70, v0
	v_mov_b32_e32 v71, v0
	v_mov_b32_e32 v80, v0
	v_mov_b32_e32 v81, v0
	v_mov_b32_e32 v82, v0
	v_mov_b32_e32 v83, v0
	v_mov_b32_e32 v84, v0
	v_mov_b32_e32 v85, v0
	v_mov_b32_e32 v86, v0
	v_mov_b32_e32 v87, v0
	v_mov_b32_e32 v88, v0
	v_mov_b32_e32 v89, v0
	v_mov_b32_e32 v90, v0
	v_mov_b32_e32 v91, v0
	v_mov_b32_e32 v92, v0
	v_mov_b32_e32 v93, v0
	v_mov_b32_e32 v94, v0
	v_mov_b32_e32 v95, v0
	v_mov_b32_e32 v100, v0
	v_mov_b32_e32 v101, v0
	v_mov_b32_e32 v102, v0
	v_mov_b32_e32 v103, v0
	v_mov_b32_e32 v108, v0
	v_mov_b32_e32 v109, v0
	v_mov_b32_e32 v110, v0
	v_mov_b32_e32 v111, v0
	v_mov_b32_e32 v72, v0
	v_mov_b32_e32 v73, v0
	v_mov_b32_e32 v74, v0
	v_mov_b32_e32 v75, v0
	v_mov_b32_e32 v76, v0
	v_mov_b32_e32 v77, v0
	v_mov_b32_e32 v78, v0
	v_mov_b32_e32 v79, v0
	v_mov_b32_e32 v96, v0
	v_mov_b32_e32 v97, v0
	v_mov_b32_e32 v98, v0
	v_mov_b32_e32 v99, v0
	v_mov_b32_e32 v104, v0
	v_mov_b32_e32 v105, v0
	v_mov_b32_e32 v106, v0
	v_mov_b32_e32 v107, v0
	v_mov_b32_e32 v112, v0
	v_mov_b32_e32 v113, v0
	v_mov_b32_e32 v114, v0
	v_mov_b32_e32 v115, v0
	v_mov_b32_e32 v116, v0
	v_mov_b32_e32 v117, v0
	v_mov_b32_e32 v118, v0
	v_mov_b32_e32 v119, v0
	v_mov_b32_e32 v120, v0
	v_mov_b32_e32 v121, v0
	v_mov_b32_e32 v122, v0
	v_mov_b32_e32 v123, v0
	v_mov_b32_e32 v124, v0
	v_mov_b32_e32 v125, v0
	v_mov_b32_e32 v126, v0
	v_mov_b32_e32 v127, v0
